# attention prefetch addressing: quarter-rate v_mul_lo_u32 by the constant row stride 0x900 replaced by shift-add
# baseline (speedup 1.0000x reference)
.LBB0_629:
	s_lshl_b32 s20, -1, s13
	s_andn2_b32 s22, s10, s20
	s_lshr_b32 s20, s15, s13
	s_lshl_b32 s21, s21, 5
	s_add_i32 s20, s20, s21
	s_lshr_b32 s18, s14, s13
	s_sub_i32 s23, s20, 64
	v_add_u32_e32 v26, s23, v49
	s_add_i32 s18, s18, -1
	v_min_i32_e32 v24, s18, v26
	v_cmp_lt_i32_e32 vcc, -1, v26
	v_add_u32_e32 v56, s23, v103
	v_min_i32_e32 v44, s18, v56
	v_cndmask_b32_e32 v24, 0, v24, vcc
	v_lshlrev_b32_e32 v24, s13, v24
	v_add_u32_e32 v24, s22, v24
	v_mad_u64_u32 v[24:25], s[20:21], v24, s31, v[98:99]
	global_load_dwordx4 v[36:39], v24, s[6:7] offset:768
	global_load_dwordx4 v[40:43], v24, s[6:7] offset:832
	v_add_u32_e32 v24, 16, v26
	v_min_i32_e32 v25, s18, v24
	v_cmp_lt_i32_e32 vcc, -1, v24
	v_add_u32_e32 v45, 8, v56
	v_min_i32_e32 v45, s18, v45
	v_cndmask_b32_e32 v24, 0, v25, vcc
	v_cmp_lt_i32_e32 vcc, -1, v56
	v_add_u32_e32 v57, 16, v56
	v_min_i32_e32 v57, s18, v57
	v_cndmask_b32_e32 v44, 0, v44, vcc
	v_cmp_lt_i32_e32 vcc, -9, v56
	v_add_u32_e32 v58, 24, v56
	v_min_i32_e32 v58, s18, v58
	v_cndmask_b32_e32 v45, 0, v45, vcc
	v_cmp_lt_i32_e32 vcc, s55, v56
	v_lshlrev_b32_e32 v44, s13, v44
	v_lshlrev_b32_e32 v45, s13, v45
	v_cndmask_b32_e32 v57, 0, v57, vcc
	v_cmp_lt_i32_e32 vcc, s96, v56
	v_lshlrev_b32_e32 v57, s13, v57
	v_lshlrev_b32_e32 v24, s13, v24
	v_cndmask_b32_e32 v56, 0, v58, vcc
	v_lshlrev_b32_e32 v56, s13, v56
	v_add_u32_e32 v44, s22, v44
	v_add_u32_e32 v45, s22, v45
	v_add_u32_e32 v57, s22, v57
	v_add_u32_e32 v56, s22, v56
	v_add_u32_e32 v24, s22, v24
	v_lshlrev_b32_e32 v114, 8, v44
	v_lshl_add_u32 v44, v44, 11, v114
	v_lshlrev_b32_e32 v115, 8, v45
	v_lshl_add_u32 v45, v45, 11, v115
	v_lshlrev_b32_e32 v116, 8, v57
	v_lshl_add_u32 v57, v57, 11, v116
	v_lshlrev_b32_e32 v117, 8, v56
	v_lshl_add_u32 v56, v56, 11, v117
	v_mad_u64_u32 v[28:29], s[20:21], v24, s31, v[98:99]
	v_or_b32_e32 v44, v44, v104
	v_or_b32_e32 v52, v45, v104
	v_or_b32_e32 v57, v57, v104
	v_or_b32_e32 v60, v56, v104
	global_load_dwordx4 v[24:27], v28, s[6:7] offset:768
	s_nop 0
	global_load_dwordx4 v[28:31], v28, s[6:7] offset:832
	s_nop 0
	global_load_dwordx4 v[44:47], v44, s[6:7] offset:1536
	s_nop 0
	global_load_dwordx4 v[52:55], v52, s[6:7] offset:1536
	s_nop 0
	global_load_dwordx4 v[56:59], v57, s[6:7] offset:1536
	s_nop 0
	global_load_dwordx4 v[60:63], v60, s[6:7] offset:1536
	s_lshr_b32 s13, s15, s12
	v_lshrrev_b32_e32 v112, s12, v110
	s_lshl_b32 s18, s19, 5
	s_lshr_b32 s19, s14, s12
	s_lshr_b32 s12, s12, 1
	s_waitcnt vmcnt(11)
	ds_write_b128 v108, v[84:87] offset:16384
	s_waitcnt vmcnt(10)
	ds_write_b128 v108, v[80:83] offset:17536
	s_waitcnt vmcnt(9)
	ds_write_b128 v108, v[92:95] offset:18688
	s_waitcnt vmcnt(8)
	ds_write_b128 v108, v[88:91] offset:19840
	v_add_u32_e32 v80, s13, v105
	v_sub_u32_e32 v81, v80, v112
	s_mul_i32 s12, s12, 6
	v_add_u32_e32 v81, s18, v81
	s_add_i32 s12, s12, s1
	s_mulk_i32 s12, 0x210
	v_add_u32_e32 v83, 1, v81
	v_add_u32_e32 v85, 2, v81
	v_add_u32_e32 v87, 3, v81
	v_add_u32_e32 v89, 16, v81
	v_add_u32_e32 v91, 17, v81
	v_add_u32_e32 v93, 18, v81
	v_add_u32_e32 v95, 19, v81
	s_add_i32 s12, s12, 0
	v_med3_i32 v82, v81, s30, 64
	v_med3_i32 v84, v83, s30, 64
	v_med3_i32 v86, v85, s30, 64
	v_med3_i32 v88, v87, s30, 64
	v_med3_i32 v90, v89, s30, 64
	v_med3_i32 v92, v91, s30, 64
	v_med3_i32 v94, v93, s30, 64
	v_med3_i32 v113, v95, s30, 64
	v_lshl_add_u32 v82, v82, 2, s12
	v_lshl_add_u32 v84, v84, 2, s12
	v_lshl_add_u32 v86, v86, 2, s12
	v_lshl_add_u32 v88, v88, 2, s12
	v_lshl_add_u32 v90, v90, 2, s12
	v_lshl_add_u32 v92, v92, 2, s12
	v_lshl_add_u32 v94, v94, 2, s12
	v_lshl_add_u32 v113, v113, 2, s12
	ds_read_b32 v82, v82 offset:256
	ds_read_b32 v84, v84 offset:256
	ds_read_b32 v86, v86 offset:256
	ds_read_b32 v88, v88 offset:256
	ds_read_b32 v90, v90 offset:256
	ds_read_b32 v92, v92 offset:256
	ds_read_b32 v94, v94 offset:256
	ds_read_b32 v113, v113 offset:256
	s_waitcnt lgkmcnt(7)
	s_waitcnt lgkmcnt(6)
	s_waitcnt lgkmcnt(5)
	s_waitcnt lgkmcnt(4)
	s_waitcnt lgkmcnt(3)
	s_waitcnt lgkmcnt(2)
	s_waitcnt lgkmcnt(1)
	s_waitcnt lgkmcnt(0)
	s_setprio 1
	v_mfma_f32_16x16x32_bf16 v[76:79], v[76:79], v[16:19], 0
	v_mfma_f32_16x16x32_bf16 v[72:75], v[72:75], v[20:23], v[76:79]
	s_setprio 0
	s_nop 5
	v_add_u32_e32 v76, s18, v80
	v_add_u32_e32 v77, 64, v81
	v_cmp_gt_u32_e32 vcc, s97, v77
	v_cmp_gt_u32_e64 s[38:39], s19, v76
	v_fmac_f32_e32 v82, 0x3e000000, v72
	s_and_b64 vcc, vcc, s[38:39]
	v_add_u32_e32 v76, v83, v112
	v_add_u32_e32 v77, 0x41, v81
	v_cndmask_b32_e32 v72, v233, v82, vcc
	v_cmp_gt_u32_e32 vcc, s97, v77
	v_cmp_gt_u32_e64 s[38:39], s19, v76
	v_fmac_f32_e32 v84, 0x3e000000, v73
	s_and_b64 vcc, vcc, s[38:39]
	v_add_u32_e32 v76, v85, v112
	v_add_u32_e32 v77, 0x42, v81
	v_cndmask_b32_e32 v73, v233, v84, vcc
	v_cmp_gt_u32_e32 vcc, s97, v77
	v_cmp_gt_u32_e64 s[38:39], s19, v76
	v_fmac_f32_e32 v86, 0x3e000000, v74
	s_and_b64 vcc, vcc, s[38:39]
	v_add_u32_e32 v76, v87, v112
	v_add_u32_e32 v77, 0x43, v81
	v_cndmask_b32_e32 v74, v233, v86, vcc
	v_cmp_gt_u32_e32 vcc, s97, v77
	v_cmp_gt_u32_e64 s[38:39], s19, v76
	v_fmac_f32_e32 v88, 0x3e000000, v75
	s_and_b64 vcc, vcc, s[38:39]
	v_cndmask_b32_e32 v75, v233, v88, vcc
	s_setprio 1
	v_mfma_f32_16x16x32_bf16 v[68:71], v[68:71], v[16:19], 0
	v_mfma_f32_16x16x32_bf16 v[64:67], v[64:67], v[20:23], v[68:71]
	s_setprio 0
	s_nop 5
	v_add_u32_e32 v68, v89, v112
	v_add_u32_e32 v69, 0x50, v81
	v_cmp_gt_u32_e32 vcc, s97, v69
	v_cmp_gt_u32_e64 s[38:39], s19, v68
	v_fmac_f32_e32 v90, 0x3e000000, v64
	s_and_b64 vcc, vcc, s[38:39]
	v_add_u32_e32 v68, v91, v112
	v_add_u32_e32 v69, 0x51, v81
	v_cndmask_b32_e32 v64, v233, v90, vcc
	v_cmp_gt_u32_e32 vcc, s97, v69
	v_cmp_gt_u32_e64 s[38:39], s19, v68
	v_fmac_f32_e32 v92, 0x3e000000, v65
	s_and_b64 vcc, vcc, s[38:39]
	v_add_u32_e32 v68, v93, v112
	v_add_u32_e32 v69, 0x52, v81
	v_cndmask_b32_e32 v65, v233, v92, vcc
	v_cmp_gt_u32_e32 vcc, s97, v69
	v_cmp_gt_u32_e64 s[38:39], s19, v68
	v_fmac_f32_e32 v94, 0x3e000000, v66
	s_and_b64 vcc, vcc, s[38:39]
	v_add_u32_e32 v68, v95, v112
	v_add_u32_e32 v69, 0x53, v81
	v_cndmask_b32_e32 v66, v233, v94, vcc
	v_cmp_gt_u32_e32 vcc, s97, v69
	v_cmp_gt_u32_e64 s[38:39], s19, v68
	v_max_f32_e32 v68, v72, v73
	v_fmac_f32_e32 v113, 0x3e000000, v67
	s_and_b64 vcc, vcc, s[38:39]
	v_max3_f32 v68, v68, v74, v75
	v_cndmask_b32_e32 v67, v233, v113, vcc
	v_max3_f32 v68, v68, v64, v65
	v_max3_f32 v68, v68, v66, v67
	v_add_f32_e32 v69, 0x41000000, v109
	v_cmp_gt_f32_e32 vcc, v68, v69
	s_cmp_lg_u64 vcc, 0
	s_cselect_b64 s[12:13], -1, 0
	s_cbranch_vccz .LBB0_631
	v_and_b32_e32 v70, 64, v234
	v_xor_b32_e32 v69, 16, v234
	v_add_u32_e32 v70, 64, v70
	v_cmp_lt_i32_e32 vcc, v69, v70
	s_nop 1
	v_cndmask_b32_e32 v69, v234, v69, vcc
	v_lshlrev_b32_e32 v69, 2, v69
	ds_bpermute_b32 v69, v69, v68
	v_max_f32_e32 v68, v68, v68
	s_waitcnt lgkmcnt(0)
	v_max_f32_e32 v69, v69, v69
	v_max_f32_e32 v68, v68, v69
	v_xor_b32_e32 v69, 32, v234
	v_cmp_lt_i32_e32 vcc, v69, v70
	s_nop 1
	v_cndmask_b32_e32 v69, v234, v69, vcc
	v_lshlrev_b32_e32 v69, 2, v69
	ds_bpermute_b32 v69, v69, v68
	s_waitcnt lgkmcnt(0)
	v_max3_f32 v69, v109, v68, v69
	v_sub_f32_e32 v68, v109, v69
	v_mul_f32_e32 v68, 0x3fb8aa3b, v68
	v_exp_f32_e32 v68, v68
	v_mov_b32_e32 v109, v69
	s_branch .LBB0_632
